# hgrn output set-up: group-norm weights / lower-bound logits prefetched (pointers at attention end, values at the S5 output pass start) instead of two dependent chases before the first item
# baseline (speedup 1.0000x reference)
; #define RELAUNDER() do { int t_ = threadIdx.x; asm volatile("" : "+v"(t_)); tid = t_; lane = tid & 63; wave = __builtin_amdgcn_readfirstlane(tid >> 6); } while (0)
; #define REPS(bit) for (int rep_ = 0; rep_ < 1 + ((MK_REP >> (bit)) & 1); ++rep_)
; __global__ void __launch_bounds__(NWAVES * 64, 2) hymba_fwd(Args args) {
;     ...
;             if (EN(4)) REPS(4) for (int v = vcu; v < 256; v += G) { const attn_body::StaticOrder S(v); attn_body::attn_phase<attn_body::StaticOrder>((char*)lds_raw, AT, S); }
;         }
;         ++ph; RELAUNDER();
;         if (IN(ph)) {
;             __syncthreads();
;             if (wave == 0) { unsigned* scnt = (unsigned*)(ws + WS_SCNT) + layer * 64; unsigned spins = 0;
;                 while ((unsigned)__builtin_amdgcn_readfirstlane(__hip_atomic_load(scnt, __ATOMIC_RELAXED, __HIP_MEMORY_SCOPE_AGENT)) < 544u) { __builtin_amdgcn_s_sleep(4); if (++spins > (1u << 22)) break; }
;                 __builtin_amdgcn_fence(__ATOMIC_ACQUIRE, "agent"); asm volatile("s_waitcnt vmcnt(0)" ::: "memory"); }
.LBB0_577:
	v_readlane_b32 s54, v254, 56
	v_readlane_b32 s48, v254, 16
	s_andn2_b64 vcc, exec, s[0:1]
	v_readlane_b32 s36, v254, 40
	v_readlane_b32 s52, v254, 54
	v_readlane_b32 s53, v254, 55
	v_readlane_b32 s55, v254, 57
	v_readlane_b32 s25, v253, 9
	v_readlane_b32 s30, v254, 59
	v_readlane_b32 s49, v254, 17
	v_mov_b32_e32 v154, 0x3800000
	v_readlane_b32 s37, v254, 41
	s_cbranch_vccnz .LBB0_810
	v_readlane_b32 s98, v253, 29
	v_readlane_b32 s99, v253, 30
	s_nop 4
	global_load_dwordx2 v[198:199], v221, s[98:99]
	v_readlane_b32 s98, v253, 12
	v_readlane_b32 s99, v253, 13
	s_nop 4
	global_load_dwordx2 v[222:223], v221, s[98:99]
	s_cmp_gt_u32 s8, 63
	s_barrier
	s_cbranch_scc1 .LBB0_671
	v_readlane_b32 s0, v254, 44
	s_lshl_b32 s62, s0, 6
	s_lshl_b64 s[0:1], s[62:63], 2
	v_readlane_b32 s2, v253, 14
	s_add_u32 s0, s2, s0
	v_readlane_b32 s2, v253, 15
	s_addc_u32 s1, s2, s1
	s_mov_b32 s9, 0x400001
	s_branch .LBB0_664

; #define LAS __attribute__((address_space(3)))
; template <bool OUT> __device__ __forceinline__ void hgrn_item2(const PA& a, LAS unsigned char* lds, int layer, int bh, int c, int wave, int lane, const HRaw& raw) {
;     ...
;         float gn[4];
; #pragma unroll
;         for (int nt = 0; nt < 4; ++nt) gn[nt] = a.in[5][layer * 64 + 16 * nt + l15];
; template <bool OUT> __device__ __forceinline__ void s5_item(const PA& a, LAS unsigned char* lds, int layer, int item, int wave, int lane) {
;     const int b = item >> 10, g = (item >> 6) & 15, c = item & 63, lg = layer * 16 + g;
;     const bf16* PROJ = (const bf16*)(a.ws + WS_PROJ);
;     const float* sa = (const float*)(a.ws + WS_S5A) + (size_t)lg * 256;
;     float* XL = (float*)(a.ws + WS_XLOC) + (size_t)((b * 16 + g) * 64) * 128;
;     const float ar = sa[lane], ai = sa[64 + lane];
;     float xr = 0.f, xi = 0.f;
;     if (OUT) { xr = XL[c * 128 + lane]; xi = XL[c * 128 + 64 + lane]; }
;     const int l15 = lane & 15, quad = lane >> 4;
;     const bf16x8 zero8 = {0, 0, 0, 0, 0, 0, 0, 0};
;     bf16x8 bfr[8];
; #pragma unroll
;     for (int nt = 0; nt < 8; ++nt) bfr[nt] = (quad < 2) ? *(const bf16x8*)((const bf16*)(a.ws + WS_S5B) + (size_t)lg * 2048 + (nt * 16 + l15) * 16 + quad * 8) : zero8;
;     bf16x8 cfr[4];
;     if (OUT) {
; #pragma unroll
;         for (int ks = 0; ks < 4; ++ks) cfr[ks] = *(const bf16x8*)((const bf16*)(a.ws + WS_S5C) + (size_t)lg * 2048 + l15 * 128 + ks * 32 + quad * 8);
;     }
;     const float dsk = a.in[13][layer * 256 + g * 16 + l15];
;     LAS float* BU = (LAS float*)(lds + wave * 12800);
;     LAS bf16* X = (LAS bf16*)(lds + wave * 12800 + 8448);
;     const size_t rowb = (size_t)b * T + (size_t)c * 128;
.LBB0_671:
	s_ashr_i32 s2, s8, 6
	v_readlane_b32 s0, v253, 6
	s_add_i32 s12, s2, s0
	s_cmpk_gt_i32 s12, 0x7ff
	s_barrier
	s_cbranch_scc1 .LBB0_705
	v_readlane_b32 s8, v252, 20
	v_and_b32_e32 v91, 63, v0
	v_and_b32_e32 v90, 15, v0
	v_bfe_u32 v4, v0, 4, 2
	v_and_b32_e32 v0, 48, v0
	v_mov_b32_e32 v1, v221
	v_readlane_b32 s9, v252, 21
	v_readlane_b32 s3, v254, 44
	v_lshlrev_b32_e32 v2, 8, v90
	v_lshl_add_u64 v[96:97], s[8:9], 0, v[0:1]
	v_readlane_b32 s8, v253, 21
	v_mov_b32_e32 v3, v221
	v_readlane_b32 s9, v253, 22
	s_lshl_b32 s13, s3, 4
	v_lshl_or_b32 v93, s3, 8, v90
	v_lshl_add_u64 v[2:3], s[8:9], 0, v[2:3]
	s_mul_i32 s3, s2, 0x3200
	v_lshlrev_b32_e32 v220, 2, v91
	v_lshl_add_u64 v[98:99], v[2:3], 0, v[0:1]
	s_add_i32 s3, s3, 0
	v_lshlrev_b32_e32 v2, 1, v91
	v_lshlrev_b32_e32 v100, 2, v4
	v_mov_b32_e32 v1, s3
	v_lshl_add_u32 v5, v90, 2, s3
	v_add_u32_e32 v95, s3, v220
	v_sub_u32_e32 v8, 0, v2
	s_lshl_b32 s2, s2, 7
	v_readlane_b32 s3, v254, 14
	v_mul_u32_u24_e32 v2, 0x1c00, v90
	v_readlane_b32 s0, v252, 18
	v_or_b32_e32 v102, 1, v100
	s_movk_i32 s8, 0x110
	s_add_i32 s14, s3, s2
	v_mul_hi_u32_u24_e32 v3, 0x1c00, v90
	v_or_b32_e32 v2, v2, v0
	s_mov_b64 s[2:3], 0x4038800
	v_readlane_b32 s1, v252, 19
	v_mul_u32_u24_e32 v6, 0x840, v4
	v_mul_u32_u24_e32 v7, 0x210, v102
	v_mad_u32_u24 v1, v90, s8, v1
	v_lshl_add_u64 v[112:113], v[2:3], 0, s[2:3]
	v_mul_u32_u24_e32 v2, 0x7000, v4
	v_lshl_add_u64 v[88:89], s[0:1], 0, v[220:221]
	v_cmp_gt_u32_e64 s[0:1], 32, v91
	v_lshlrev_b32_e32 v92, 4, v90
	v_lshlrev_b32_e32 v94, 3, v4
	v_cmp_lt_u32_e64 s[38:39], 31, v91
	v_mov_b32_e32 v101, v221
	v_or_b32_e32 v104, 2, v100
	v_or_b32_e32 v106, 3, v100
	v_or_b32_e32 v108, 16, v91
	v_lshlrev_b32_e32 v110, 11, v4
	v_mul_hi_u32_u24_e32 v115, 0x7000, v4
	v_lshl_or_b32 v114, v90, 1, v2
	v_lshlrev_b32_e32 v116, 1, v90
	v_add_u32_e32 v103, v1, v0
	v_add_u32_e32 v105, v5, v6
	v_add_u32_e32 v107, v5, v7
	v_add_u32_e32 v109, v95, v8
	s_waitcnt vmcnt(0)
	v_and_b32_e32 v228, 15, v234
	v_readlane_b32 s8, v254, 44
	s_nop 1
	v_lshl_or_b32 v228, s8, 6, v228
	v_lshlrev_b32_e32 v228, 2, v228
	v_mov_b32_e32 v229, 0
	v_lshl_add_u64 v[198:199], v[228:229], 0, v[198:199]
	v_readlane_b32 s8, v252, 0
	s_bfe_u32 s8, s8, 0x20005
	v_and_b32_e32 v228, 63, v234
	v_lshlrev_b32_e32 v228, 2, v228
	v_lshl_or_b32 v228, s8, 8, v228
	v_lshl_add_u64 v[222:223], v[228:229], 0, v[222:223]
	global_load_dword v230, v[198:199], off
	global_load_dword v231, v[198:199], off offset:64
	global_load_dword v232, v[198:199], off offset:128
	global_load_dword v227, v[198:199], off offset:192
	global_load_dword v228, v[222:223], off offset:1024
	global_load_dword v229, v[222:223], off
	v_readlane_b32 s8, v253, 23
	v_readlane_b32 s9, v253, 24
	s_nop 4
	global_load_dwordx2 v[194:195], v221, s[8:9]
	s_branch .LBB0_674

; #define LAS __attribute__((address_space(3)))
; #define LDS_WAIT() asm volatile("s_waitcnt lgkmcnt(0)" ::: "memory")
; __device__ __forceinline__ float sigmf(float v) { return __builtin_amdgcn_rcpf(1.0f + __builtin_amdgcn_exp2f(-1.4426950408889634f * v)); }
; template <bool OUT> __device__ __forceinline__ void hgrn_item2(const PA& a, LAS unsigned char* lds, int layer, int bh, int c, int wave, int lane, const HRaw& raw) {
;     const int b = bh >> 2, h = bh & 3, item = bh * 64 + c;
;     float* HU = (float*)(a.ws + WS_HU); float* HA = (float*)(a.ws + WS_HA);
;     LAS unsigned char* wb = lds + wave * 12288;
;     LAS bf16* QT = (LAS bf16*)wb; LAS bf16* KT = (LAS bf16*)(wb + 2304); LAS bf16* KHT = (LAS bf16*)(wb + 4608); LAS bf16* VT = (LAS bf16*)(wb + 7680); LAS bf16* P = (LAS bf16*)(wb + 10752);
;     LAS float* DL = (LAS float*)(wb + 11520); LAS float* E7L = (LAS float*)(wb + 11776);
;     LAS bf16* RF = (LAS bf16*)wb; LAS bf16* RV = (LAS bf16*)(wb + 2304); LAS bf16* RQ = (LAS bf16*)(wb + 4608);
;     LAS bf16* GT = KHT; LAS bf16* OT = VT;
;     LAS float* SBUF = (LAS float*)(lds + 98304); LAS float* DALL = (LAS float*)(lds + 114688);
;     const int l15 = lane & 15, q = lane >> 4;
;     const size_t row0 = (size_t)b * T + (size_t)c * 128 + wave * 16;
;     const bf16x8 zero8 = {0, 0, 0, 0, 0, 0, 0, 0};
;     __syncthreads();
;     {
;         const int rr = lane >> 3, cc = (lane & 7) * 8;
; #pragma unroll
;         for (int k = 0; k < 2; ++k) { *(LAS v4u*)(RF + (rr + 8 * k) * 72 + cc) = raw.f[k]; *(LAS v4u*)(RV + (rr + 8 * k) * 72 + cc) = raw.v[k]; if (OUT) *(LAS v4u*)(RQ + (rr + 8 * k) * 72 + cc) = raw.q[k]; }
;         LDS_WAIT();
;         const float lb = (layer == 0) ? 0.f : sigmf(a.in[4][256 + h * 64 + lane] - a.in[4][h * 64 + lane]);
;     ...
;         float gn[4];
; #pragma unroll
;         for (int nt = 0; nt < 4; ++nt) gn[nt] = a.in[5][layer * 64 + 16 * nt + l15];
.LBB0_705:
	v_readlane_b32 s0, v253, 7
	v_mov_b32_e32 v0, v234
	v_readlane_b32 s1, v253, 8
	s_andn2_b64 vcc, exec, s[0:1]
	v_readfirstlane_b32 s0, v0
	s_cbranch_vccnz .LBB0_756
	s_ashr_i32 s2, s0, 6
	s_lshl_b32 s0, s2, 4
	v_bfe_u32 v1, v0, 3, 3
	v_and_b32_e32 v200, 63, v0
	s_ashr_i32 s1, s0, 31
	v_or_b32_e32 v188, s0, v1
	v_lshlrev_b32_e32 v2, 3, v0
	s_mul_i32 s0, s2, 0x3000
	v_and_b32_e32 v2, 56, v2
	s_add_i32 s3, s0, 0
	v_mul_u32_u24_e32 v1, 0x48, v1
	v_lshlrev_b32_e32 v5, 1, v200
	v_lshlrev_b32_e32 v4, 1, v2
	v_lshlrev_b32_e32 v1, 1, v1
	v_add_u32_e32 v202, s3, v5
	v_add3_u32 v201, s3, v4, v1
	v_add_u32_e32 v203, v202, v5
	v_or_b32_e32 v5, 16, v200
	v_add3_u32 v204, s3, v1, v4
	v_bfe_u32 v4, v0, 2, 4
	v_mul_u32_u24_e32 v12, 48, v5
	v_or_b32_e32 v5, 48, v200
	v_and_b32_e32 v14, 12, v4
	v_and_b32_e32 v3, 15, v0
	v_mul_u32_u24_e32 v13, 48, v5
	v_or_b32_e32 v5, 1, v14
	v_mul_u32_u24_e32 v1, 0x48, v3
	v_cmp_gt_u32_e64 s[42:43], v3, v5
	v_or_b32_e32 v5, 2, v14
	v_or_b32_e32 v16, 3, v4
	v_lshl_or_b32 v4, s2, 7, v200
	v_lshl_add_u32 v1, v1, 1, s3
	s_movk_i32 s0, 0xff72
	v_cmp_gt_u32_e64 s[44:45], v3, v5
	v_ashrrev_i32_e32 v5, 31, v4
	v_lshl_add_u32 v205, v14, 1, v1
	v_mad_i32_i24 v1, v3, s0, v1
	v_lshlrev_b64 v[224:225], 4, v[4:5]
	v_or_b32_e32 v6, 64, v4
	v_lshlrev_b32_e32 v206, 4, v4
	v_readlane_b32 s0, v254, 44
	v_mul_u32_u24_e32 v4, 0x48, v14
	v_or_b32_e32 v4, v4, v3
	v_lshl_or_b32 v194, s0, 6, v3
	s_movk_i32 s0, 0x48
	v_lshl_add_u32 v209, v4, 1, s3
	v_mad_u32_u24 v4, v14, s0, s0
	v_mul_u32_u24_e32 v11, 48, v3
	v_cmp_gt_u32_e64 s[40:41], v3, v14
	v_cmp_gt_u32_e64 s[46:47], v3, v16
	v_mad_u32_u24 v18, v3, 48, s3
	v_add_u32_e32 v3, v4, v3
	v_and_b32_e32 v9, 16, v0
	v_lshl_add_u32 v3, v3, 1, s3
	v_mul_u32_u24_e32 v8, 44, v200
	v_add_u32_e32 v10, s3, v9
	v_mul_u32_u24_e32 v15, 48, v14
	v_mul_u32_u24_e32 v17, 48, v16
	v_ashrrev_i32_e32 v7, 31, v6
	v_and_b32_e32 v208, 48, v0
	v_lshlrev_b32_e32 v0, 4, v200
	v_add_u32_e32 v211, 0x90, v3
	v_mul_u32_u24_e32 v3, 0x48, v16
	v_mov_b32_e32 v189, s1
	v_cmp_gt_u32_e64 s[38:39], 32, v200
	v_lshlrev_b64 v[240:241], 4, v[6:7]
	v_lshlrev_b32_e32 v207, 4, v6
	v_mov_b32_e32 v195, v221
	v_lshl_add_u32 v210, v4, 1, v1
	v_lshl_add_u32 v212, v3, 1, v1
	v_lshlrev_b32_e32 v220, 1, v2
	v_add_u32_e32 v213, v203, v8
	v_add_u32_e32 v214, v10, v11
	v_add_u32_e32 v215, v10, v12
	v_add_u32_e32 v216, v10, v13
	v_add_u32_e32 v217, v1, v15
	v_add_u32_e32 v218, v1, v17
	v_add_u32_e32 v219, v18, v9
	v_add_u32_e32 v226, 0, v0
	v_readlane_b32 s0, v253, 29
	v_readlane_b32 s1, v253, 30
	v_readlane_b32 s14, v253, 12
	v_readlane_b32 s15, v253, 13
	v_readlane_b32 s8, v252, 0
	s_bfe_u32 s8, s8, 0x20005
	v_lshlrev_b32_e32 v24, 2, v200
	v_lshl_or_b32 v24, s8, 8, v24
	v_mov_b32_e32 v25, v221
	s_waitcnt vmcnt(0)
	v_mov_b32_e32 v28, v230
	v_mov_b32_e32 v29, v231
	v_mov_b32_e32 v27, v232
	v_mov_b32_e32 v26, v227
	v_mov_b32_e32 v30, 0
	s_andn2_b64 vcc, exec, s[4:5]
	s_cbranch_vccnz .Lmy_ho_nolb
	v_mov_b32_e32 v30, v228
	v_mov_b32_e32 v31, v229
	v_sub_f32_e32 v30, v30, v31
	v_mul_f32_e32 v30, 0xbfb8aa3b, v30
	v_exp_f32_e32 v30, v30
	s_nop 0
	v_add_f32_e32 v30, 1.0, v30
	v_rcp_f32_e32 v30, v30
